# v15 + mixer B first gate load issued at item start instead of an exposed round trip before its use
# speedup vs baseline: 1.0131x; 1.0018x over previous
.LBB0_1252:
	s_or_b64 exec, exec, s[8:9]
	s_lshl_b32 s8, s7, 3
	s_or_b32 s8, s8, s56
	s_bfe_u32 s66, s8, 0x30001
	v_ashrrev_i32_e32 v86, 3, v87
	v_lshl_add_u32 v2, s66, 7, v86
	v_lshlrev_b32_e32 v0, 4, v84
	v_ashrrev_i32_e32 v3, 31, v2
	v_and_b32_e32 v131, 0x70, v0
	v_lshlrev_b64 v[10:11], 8, v[2:3]
	s_lshl_b32 s46, s6, 1
	v_or3_b32 v10, v131, s46, v10
	s_mov_b64 s[8:9], 0x4000
	v_lshl_add_u64 v[2:3], s[58:59], 0, v[10:11]
	v_lshl_add_u64 v[6:7], s[60:61], 0, v[10:11]
	v_lshl_add_u64 v[10:11], v[10:11], 0, s[8:9]
	v_lshl_add_u64 v[12:13], s[58:59], 0, v[10:11]
	v_lshl_add_u64 v[14:15], s[60:61], 0, v[10:11]
	global_load_dwordx4 v[2:5], v[2:3], off
	s_nop 0
	global_load_dwordx4 v[6:9], v[6:7], off
	s_nop 0
	global_load_dwordx4 v[10:13], v[12:13], off
	s_nop 0
	global_load_dwordx4 v[14:17], v[14:15], off
	s_lshl_b32 s7, s7, 4
	s_andn2_b32 s7, s7, 31
	s_sub_i32 s16, 0x7e0, s7
	v_and_b32_e32 v85, 31, v84
	v_or_b32_e32 v193, s16, v85
	v_ashrrev_i32_e32 v0, 5, v84
	v_lshl_add_u32 v132, s66, 11, v193
	v_mov_b64_e32 v[18:19], s[50:51]
	v_mad_i64_i32 v[82:83], s[8:9], v132, s84, v[18:19]
	s_lshl_b32 s72, s34, 1
	s_mov_b32 s73, s67
	v_lshlrev_b32_e32 v20, 3, v0
	v_lshl_add_u64 v[18:19], v[82:83], 0, s[72:73]
	v_ashrrev_i32_e32 v21, 31, v20
	v_lshl_add_u64 v[18:19], v[20:21], 1, v[18:19]
	global_load_dwordx4 v[98:101], v[18:19], off offset:2560
	global_load_dwordx4 v[102:105], v[18:19], off offset:2592
	global_load_dwordx4 v[106:109], v[18:19], off offset:2624
	global_load_dwordx4 v[110:113], v[18:19], off offset:2656
	v_lshrrev_b32_e32 v18, 2, v84
	v_lshlrev_b32_e32 v130, 2, v0
	v_mul_lo_u32 v194, v86, s86
	v_mul_lo_u32 v21, v86, 48
	v_and_or_b32 v22, v18, 3, v130
	v_add_u32_e32 v18, 0, v194
	v_lshlrev_b32_e32 v19, 1, v84
	v_add_u32_e32 v135, v18, v131
	v_add_u32_e32 v18, v18, v21
	s_movk_i32 s8, 0xffd0
	v_and_b32_e32 v20, 32, v19
	v_mad_u32_u24 v19, v85, s86, 0
	v_lshlrev_b32_e32 v195, 4, v0
	v_add_u32_e32 v134, v18, v131
	v_add_u32_e32 v42, v19, v195
	v_mad_u64_u32 v[18:19], s[8:9], v86, s8, v[134:135]
	v_add_u32_e32 v19, v18, v21
	s_waitcnt vmcnt(7)
	ds_write_b128 v135, v[2:5]
	s_waitcnt vmcnt(6)
	ds_write_b128 v134, v[6:9] offset:9216
	s_waitcnt vmcnt(5)
	ds_write_b128 v18, v[10:13] offset:21504
	s_waitcnt vmcnt(4)
	ds_write_b128 v19, v[14:17] offset:30720
	v_mov_b32_e32 v242, 0x1affc
	v_mov_b32_e32 v243, 0xf149f2ca
	ds_write_b32 v242, v243
	s_waitcnt lgkmcnt(0)
	s_barrier
	ds_read_b128 v[2:5], v42
	ds_read_b128 v[34:37], v42 offset:32
	ds_read_b128 v[6:9], v42 offset:4608
	ds_read_b128 v[38:41], v42 offset:4640
	ds_read_b128 v[44:47], v42 offset:64
	ds_read_b128 v[48:51], v42 offset:96
	ds_read_b128 v[52:55], v42 offset:4672
	ds_read_b128 v[56:59], v42 offset:4704
	v_lshlrev_b32_e32 v10, 3, v84
	v_and_b32_e32 v10, 24, v10
	v_mul_lo_u32 v11, v22, s85
	v_or3_b32 v196, v11, v20, v10
	s_waitcnt vmcnt(3) lgkmcnt(7)
	v_mfma_f32_32x32x16_bf16 v[18:33], v[2:5], v[98:101], 0
	s_waitcnt lgkmcnt(5)
	v_mfma_f32_32x32x16_bf16 v[2:17], v[6:9], v[98:101], 0
	s_waitcnt vmcnt(2)
	v_mfma_f32_32x32x16_bf16 v[18:33], v[34:37], v[102:105], v[18:33]
	s_waitcnt lgkmcnt(4)
	v_mfma_f32_32x32x16_bf16 v[2:17], v[38:41], v[102:105], v[2:17]
	s_waitcnt vmcnt(1) lgkmcnt(3)
	v_mfma_f32_32x32x16_bf16 v[18:33], v[44:47], v[106:109], v[18:33]
	v_add_u32_e32 v89, 0, v196
	ds_read_b64_tr_b16 v[34:35], v89 offset:9216
	ds_read_b64_tr_b16 v[36:37], v89 offset:10752
	ds_read_b64_tr_b16 v[40:41], v89 offset:10816
	ds_read_b64_tr_b16 v[38:39], v89 offset:9280
	v_subrev_u32_e32 v88, 31, v193
	v_lshlrev_b32_e32 v45, 6, v0
	v_sub_u32_e32 v46, v88, v45
	v_cmp_lt_i32_e32 vcc, -1, v46
	v_cmp_gt_i32_e64 s[8:9], 32, v0
	s_waitcnt lgkmcnt(5)
	v_mfma_f32_32x32x16_bf16 v[2:17], v[52:55], v[106:109], v[2:17]
	s_and_b64 s[10:11], s[8:9], vcc
	v_mov_b32_e32 v43, 0xf149f2ca
	v_mov_b32_e32 v44, 0xf149f2ca
	s_waitcnt vmcnt(0)
	s_add_i32 s100, s70, 0x1800
	s_mov_b32 s101, 0
	v_lshl_add_u64 v[244:245], v[82:83], 0, s[100:101]
	global_load_ushort v246, v[244:245], off
	v_mfma_f32_32x32x16_bf16 v[18:33], v[48:51], v[110:113], v[18:33]
	s_waitcnt lgkmcnt(4)
	v_mfma_f32_32x32x16_bf16 v[2:17], v[56:59], v[110:113], v[2:17]
	v_min_u32_e32 v210, 0x7f, v46
	v_lshl_add_u32 v210, v210, 2, s3
	v_cndmask_b32_e64 v210, v242, v210, s[10:11]
	ds_read_b32 v210, v210
	v_sub_u32_e32 v74, v193, v45
	v_add_u32_e32 v150, 0xfffffde1, v74
	v_cmp_lt_i32_e64 s[8:9], -1, v150
	v_cmp_gt_i32_e32 vcc, 24, v0
	s_and_b64 s[10:11], vcc, s[8:9]
	v_min_u32_e32 v211, 0x7f, v150
	v_lshl_add_u32 v211, v211, 2, s3
	v_cndmask_b32_e64 v211, v242, v211, s[10:11]
	ds_read_b32 v211, v211
	v_or_b32_e32 v151, 1, v130
	v_lshlrev_b32_e32 v152, 4, v151
	v_sub_u32_e32 v45, v88, v152
	v_cmp_lt_i32_e64 s[8:9], -1, v45
	v_cmp_gt_i32_e64 s[10:11], s82, v151
	s_and_b64 s[10:11], s[10:11], s[8:9]
	v_min_u32_e32 v212, 0x7f, v45
	v_lshl_add_u32 v212, v212, 2, s3
	v_cndmask_b32_e64 v212, v242, v212, s[10:11]
	ds_read_b32 v212, v212
	v_add_u32_e32 v153, 0xfffffdd1, v74
	v_cmp_lt_i32_e64 s[8:9], -1, v153
	s_and_b64 s[10:11], vcc, s[8:9]
	v_min_u32_e32 v213, 0x7f, v153
	v_lshl_add_u32 v213, v213, 2, s3
	v_cndmask_b32_e64 v213, v242, v213, s[10:11]
	ds_read_b32 v213, v213
	v_or_b32_e32 v154, 2, v130
	v_lshlrev_b32_e32 v155, 4, v154
	v_sub_u32_e32 v45, v88, v155
	v_cmp_lt_i32_e64 s[8:9], -1, v45
	v_cmp_gt_i32_e64 s[10:11], s82, v154
	s_and_b64 s[10:11], s[10:11], s[8:9]
	v_min_u32_e32 v214, 0x7f, v45
	v_lshl_add_u32 v214, v214, 2, s3
	v_cndmask_b32_e64 v214, v242, v214, s[10:11]
	ds_read_b32 v214, v214
	v_add_u32_e32 v156, 0xfffffdc1, v74
	v_cmp_lt_i32_e64 s[8:9], -1, v156
	s_and_b64 s[10:11], vcc, s[8:9]
	v_min_u32_e32 v215, 0x7f, v156
	v_lshl_add_u32 v215, v215, 2, s3
	v_cndmask_b32_e64 v215, v242, v215, s[10:11]
	ds_read_b32 v215, v215
	v_or_b32_e32 v157, 3, v130
	v_lshlrev_b32_e32 v158, 4, v157
	v_sub_u32_e32 v45, v88, v158
	v_cmp_lt_i32_e32 vcc, -1, v45
	v_cmp_gt_i32_e64 s[8:9], s82, v157
	s_and_b64 s[10:11], s[8:9], vcc
	v_min_u32_e32 v216, 0x7f, v45
	v_lshl_add_u32 v216, v216, 2, s3
	v_cndmask_b32_e64 v216, v242, v216, s[10:11]
	ds_read_b32 v216, v216
	v_add_u32_e32 v159, 0xfffffdb1, v74
	v_cmp_lt_i32_e32 vcc, -1, v159
	v_cmp_gt_i32_e64 s[8:9], 23, v0
	s_and_b64 s[10:11], s[8:9], vcc
	v_min_u32_e32 v217, 0x7f, v159
	v_lshl_add_u32 v217, v217, 2, s3
	v_cndmask_b32_e64 v217, v242, v217, s[10:11]
	ds_read_b32 v217, v217
	v_add_u32_e32 v45, 0xffffff61, v74
	v_cmp_lt_i32_e64 s[8:9], -1, v45
	v_cmp_gt_i32_e32 vcc, 30, v0
	s_and_b64 s[10:11], vcc, s[8:9]
	v_min_u32_e32 v218, 0x7f, v45
	v_lshl_add_u32 v218, v218, 2, s3
	v_cndmask_b32_e64 v218, v242, v218, s[10:11]
	ds_read_b32 v218, v218
	v_add_u32_e32 v160, 0xfffffd61, v74
	v_cmp_lt_i32_e64 s[10:11], -1, v160
	v_cmp_gt_i32_e64 s[8:9], 22, v0
	s_and_b64 s[12:13], s[8:9], s[10:11]
	v_min_u32_e32 v219, 0x7f, v160
	v_lshl_add_u32 v219, v219, 2, s3
	v_cndmask_b32_e64 v219, v242, v219, s[12:13]
	ds_read_b32 v219, v219
	v_add_u32_e32 v45, 0xffffff51, v74
	v_cmp_lt_i32_e64 s[10:11], -1, v45
	s_and_b64 s[12:13], vcc, s[10:11]
	v_min_u32_e32 v220, 0x7f, v45
	v_lshl_add_u32 v220, v220, 2, s3
	v_cndmask_b32_e64 v220, v242, v220, s[12:13]
	ds_read_b32 v220, v220
	v_add_u32_e32 v161, 0xfffffd51, v74
	v_cmp_lt_i32_e64 s[10:11], -1, v161
	s_and_b64 s[12:13], s[8:9], s[10:11]
	v_min_u32_e32 v221, 0x7f, v161
	v_lshl_add_u32 v221, v221, 2, s3
	v_cndmask_b32_e64 v221, v242, v221, s[12:13]
	ds_read_b32 v221, v221
	v_add_u32_e32 v45, 0xffffff41, v74
	v_cmp_lt_i32_e64 s[10:11], -1, v45
	s_and_b64 s[12:13], vcc, s[10:11]
	v_min_u32_e32 v222, 0x7f, v45
	v_lshl_add_u32 v222, v222, 2, s3
	v_cndmask_b32_e64 v222, v242, v222, s[12:13]
	ds_read_b32 v222, v222
	v_add_u32_e32 v162, 0xfffffd41, v74
	v_cmp_lt_i32_e32 vcc, -1, v162
	s_and_b64 s[10:11], s[8:9], vcc
	v_min_u32_e32 v223, 0x7f, v162
	v_lshl_add_u32 v223, v223, 2, s3
	v_cndmask_b32_e64 v223, v242, v223, s[10:11]
	ds_read_b32 v223, v223
	v_add_u32_e32 v45, 0xffffff31, v74
	v_cmp_lt_i32_e32 vcc, -1, v45
	v_cmp_gt_i32_e64 s[8:9], 29, v0
	s_and_b64 s[10:11], s[8:9], vcc
	v_min_u32_e32 v224, 0x7f, v45
	v_lshl_add_u32 v224, v224, 2, s3
	v_cndmask_b32_e64 v224, v242, v224, s[10:11]
	ds_read_b32 v224, v224
	v_add_u32_e32 v163, 0xfffffd31, v74
	v_cmp_lt_i32_e32 vcc, -1, v163
	v_cmp_gt_i32_e64 s[8:9], 21, v0
	s_and_b64 s[10:11], s[8:9], vcc
	v_min_u32_e32 v225, 0x7f, v163
	v_lshl_add_u32 v225, v225, 2, s3
	v_cndmask_b32_e64 v225, v242, v225, s[10:11]
	ds_read_b32 v225, v225
	v_add_u32_e32 v45, 0xfffffee1, v74
	v_cmp_lt_i32_e64 s[8:9], -1, v45
	v_cmp_gt_i32_e32 vcc, 28, v0
	s_and_b64 s[10:11], vcc, s[8:9]
	v_min_u32_e32 v226, 0x7f, v45
	v_lshl_add_u32 v226, v226, 2, s3
	v_cndmask_b32_e64 v226, v242, v226, s[10:11]
	ds_read_b32 v226, v226
	v_add_u32_e32 v164, 0xfffffce1, v74
	v_cmp_lt_i32_e64 s[10:11], -1, v164
	v_cmp_gt_i32_e64 s[8:9], 20, v0
	s_and_b64 s[12:13], s[8:9], s[10:11]
	v_min_u32_e32 v227, 0x7f, v164
	v_lshl_add_u32 v227, v227, 2, s3
	v_cndmask_b32_e64 v227, v242, v227, s[12:13]
	ds_read_b32 v227, v227
	v_add_u32_e32 v45, 0xfffffed1, v74
	v_cmp_lt_i32_e64 s[10:11], -1, v45
	s_and_b64 s[12:13], vcc, s[10:11]
	v_min_u32_e32 v228, 0x7f, v45
	v_lshl_add_u32 v228, v228, 2, s3
	v_cndmask_b32_e64 v228, v242, v228, s[12:13]
	ds_read_b32 v228, v228
	v_add_u32_e32 v165, 0xfffffcd1, v74
	v_cmp_lt_i32_e64 s[10:11], -1, v165
	s_and_b64 s[12:13], s[8:9], s[10:11]
	v_min_u32_e32 v229, 0x7f, v165
	v_lshl_add_u32 v229, v229, 2, s3
	v_cndmask_b32_e64 v229, v242, v229, s[12:13]
	ds_read_b32 v229, v229
	v_add_u32_e32 v45, 0xfffffec1, v74
	v_cmp_lt_i32_e64 s[10:11], -1, v45
	s_and_b64 s[12:13], vcc, s[10:11]
	v_min_u32_e32 v230, 0x7f, v45
	v_lshl_add_u32 v230, v230, 2, s3
	v_cndmask_b32_e64 v230, v242, v230, s[12:13]
	ds_read_b32 v230, v230
	v_add_u32_e32 v166, 0xfffffcc1, v74
	v_cmp_lt_i32_e32 vcc, -1, v166
	s_and_b64 s[10:11], s[8:9], vcc
	v_min_u32_e32 v231, 0x7f, v166
	v_lshl_add_u32 v231, v231, 2, s3
	v_cndmask_b32_e64 v231, v242, v231, s[10:11]
	ds_read_b32 v231, v231
	v_add_u32_e32 v45, 0xfffffeb1, v74
	v_cmp_lt_i32_e32 vcc, -1, v45
	v_cmp_gt_i32_e64 s[8:9], 27, v0
	s_and_b64 s[10:11], s[8:9], vcc
	v_min_u32_e32 v232, 0x7f, v45
	v_lshl_add_u32 v232, v232, 2, s3
	v_cndmask_b32_e64 v232, v242, v232, s[10:11]
	ds_read_b32 v232, v232
	v_add_u32_e32 v167, 0xfffffcb1, v74
	v_cmp_lt_i32_e32 vcc, -1, v167
	v_cmp_gt_i32_e64 s[8:9], 19, v0
	s_and_b64 s[10:11], s[8:9], vcc
	v_min_u32_e32 v233, 0x7f, v167
	v_lshl_add_u32 v233, v233, 2, s3
	v_cndmask_b32_e64 v233, v242, v233, s[10:11]
	ds_read_b32 v233, v233
	v_add_u32_e32 v45, 0xfffffe61, v74
	v_cmp_lt_i32_e64 s[8:9], -1, v45
	v_cmp_gt_i32_e32 vcc, 26, v0
	s_and_b64 s[10:11], vcc, s[8:9]
	v_min_u32_e32 v234, 0x7f, v45
	v_lshl_add_u32 v234, v234, 2, s3
	v_cndmask_b32_e64 v234, v242, v234, s[10:11]
	ds_read_b32 v234, v234
	v_add_u32_e32 v168, 0xfffffc61, v74
	v_cmp_lt_i32_e64 s[10:11], -1, v168
	v_cmp_gt_i32_e64 s[8:9], 18, v0
	s_and_b64 s[12:13], s[8:9], s[10:11]
	v_min_u32_e32 v235, 0x7f, v168
	v_lshl_add_u32 v235, v235, 2, s3
	v_cndmask_b32_e64 v235, v242, v235, s[12:13]
	ds_read_b32 v235, v235
	v_add_u32_e32 v45, 0xfffffe51, v74
	v_cmp_lt_i32_e64 s[10:11], -1, v45
	s_and_b64 s[12:13], vcc, s[10:11]
	v_min_u32_e32 v236, 0x7f, v45
	v_lshl_add_u32 v236, v236, 2, s3
	v_cndmask_b32_e64 v236, v242, v236, s[12:13]
	ds_read_b32 v236, v236
	v_add_u32_e32 v169, 0xfffffc51, v74
	v_cmp_lt_i32_e64 s[10:11], -1, v169
	s_and_b64 s[12:13], s[8:9], s[10:11]
	v_min_u32_e32 v237, 0x7f, v169
	v_lshl_add_u32 v237, v237, 2, s3
	v_cndmask_b32_e64 v237, v242, v237, s[12:13]
	ds_read_b32 v237, v237
	v_add_u32_e32 v45, 0xfffffe41, v74
	v_cmp_lt_i32_e64 s[10:11], -1, v45
	s_and_b64 s[12:13], vcc, s[10:11]
	v_min_u32_e32 v238, 0x7f, v45
	v_lshl_add_u32 v238, v238, 2, s3
	v_cndmask_b32_e64 v238, v242, v238, s[12:13]
	ds_read_b32 v238, v238
	v_add_u32_e32 v170, 0xfffffc41, v74
	v_cmp_lt_i32_e32 vcc, -1, v170
	s_and_b64 s[10:11], s[8:9], vcc
	v_min_u32_e32 v239, 0x7f, v170
	v_lshl_add_u32 v239, v239, 2, s3
	v_cndmask_b32_e64 v239, v242, v239, s[10:11]
	ds_read_b32 v239, v239
	v_add_u32_e32 v45, 0xfffffe31, v74
	v_cmp_lt_i32_e32 vcc, -1, v45
	v_cmp_gt_i32_e64 s[8:9], 25, v0
	s_and_b64 s[10:11], s[8:9], vcc
	v_min_u32_e32 v240, 0x7f, v45
	v_lshl_add_u32 v240, v240, 2, s3
	v_cndmask_b32_e64 v240, v242, v240, s[10:11]
	ds_read_b32 v240, v240
	v_add_u32_e32 v171, 0xfffffc31, v74
	v_cmp_lt_i32_e32 vcc, -1, v171
	v_cmp_gt_i32_e64 s[8:9], 17, v0
	s_and_b64 s[10:11], s[8:9], vcc
	v_min_u32_e32 v241, 0x7f, v171
	v_lshl_add_u32 v241, v241, 2, s3
	v_cndmask_b32_e64 v241, v242, v241, s[10:11]
	ds_read_b32 v241, v241
	s_waitcnt lgkmcnt(0)
	v_add_f32_e32 v44, v18, v210
	v_add_f32_e32 v43, v2, v211
	v_add_f32_e32 v18, v19, v212
	v_add_f32_e32 v2, v3, v213
	v_add_f32_e32 v19, v20, v214
	v_add_f32_e32 v3, v4, v215
	v_add_f32_e32 v20, v21, v216
	v_add_f32_e32 v4, v5, v217
	v_add_f32_e32 v21, v22, v218
	v_add_f32_e32 v5, v6, v219
	v_add_f32_e32 v22, v23, v220
	v_add_f32_e32 v6, v7, v221
	v_add_f32_e32 v23, v24, v222
	v_add_f32_e32 v7, v8, v223
	v_add_f32_e32 v24, v25, v224
	v_add_f32_e32 v8, v9, v225
	v_add_f32_e32 v25, v26, v226
	v_add_f32_e32 v9, v10, v227
	v_add_f32_e32 v26, v27, v228
	v_add_f32_e32 v10, v11, v229
	v_add_f32_e32 v27, v28, v230
	v_add_f32_e32 v11, v12, v231
	v_add_f32_e32 v28, v29, v232
	v_add_f32_e32 v12, v13, v233
	v_add_f32_e32 v29, v30, v234
	v_add_f32_e32 v13, v14, v235
	v_add_f32_e32 v30, v31, v236
	v_add_f32_e32 v14, v15, v237
	v_add_f32_e32 v31, v32, v238
	v_add_f32_e32 v15, v16, v239
	v_add_f32_e32 v32, v33, v240
	v_add_f32_e32 v16, v17, v241
	v_max3_f32 v17, v191, v44, v43
	v_lshlrev_b32_e32 v33, 7, v0
	v_max3_f32 v17, v17, v18, v2
	v_lshlrev_b32_e32 v45, 2, v85
	v_max3_f32 v17, v17, v19, v3
	s_movk_i32 s8, 0x80
	v_max3_f32 v17, v17, v20, v4
	v_bitop3_b32 v197, v33, s8, v45 bitop3:0x36
	v_max3_f32 v17, v17, v21, v5
	v_mov_b32_e32 v79, 0xf149f2ca
	v_max3_f32 v17, v17, v22, v6
	v_max3_f32 v17, v17, v23, v7
	v_max3_f32 v17, v17, v24, v8
	v_max3_f32 v17, v17, v25, v9
	v_max3_f32 v17, v17, v26, v10
	v_max3_f32 v17, v17, v27, v11
	v_max3_f32 v17, v17, v28, v12
	v_max3_f32 v17, v17, v29, v13
	v_max3_f32 v17, v17, v30, v14
	v_max3_f32 v17, v17, v31, v15
	v_max3_f32 v17, v17, v32, v16
	ds_bpermute_b32 v33, v197, v17
	v_max_f32_e32 v17, v17, v17
	s_waitcnt lgkmcnt(0)
	v_max_f32_e32 v33, v33, v33
	v_max_f32_e32 v17, v17, v33
	v_max_f32_e32 v75, 0xf149f2ca, v17
	v_sub_f32_e32 v5, v5, v75
	v_exp_f32_e32 v59, v5
	v_sub_f32_e32 v5, v22, v75
	v_exp_f32_e32 v22, v5
	v_sub_f32_e32 v5, v6, v75
	v_exp_f32_e32 v60, v5
	v_sub_f32_e32 v5, v23, v75
	v_exp_f32_e32 v23, v5
	v_sub_f32_e32 v5, v7, v75
	v_sub_f32_e32 v33, v44, v75
	v_sub_f32_e32 v43, v43, v75
	v_exp_f32_e32 v61, v5
	v_sub_f32_e32 v5, v24, v75
	v_exp_f32_e32 v33, v33
	v_exp_f32_e32 v43, v43
	v_sub_f32_e32 v18, v18, v75
	v_sub_f32_e32 v2, v2, v75
	v_sub_f32_e32 v3, v3, v75
	v_exp_f32_e32 v24, v5
	v_sub_f32_e32 v5, v8, v75
	v_exp_f32_e32 v18, v18
	v_exp_f32_e32 v56, v2
	v_sub_f32_e32 v19, v19, v75
	v_exp_f32_e32 v57, v3
	v_sub_f32_e32 v3, v20, v75
	v_exp_f32_e32 v62, v5
	v_sub_f32_e32 v5, v25, v75
	v_exp_f32_e32 v19, v19
	v_exp_f32_e32 v20, v3
	v_sub_f32_e32 v3, v4, v75
	v_exp_f32_e32 v63, v5
	v_sub_f32_e32 v5, v9, v75
	v_exp_f32_e32 v58, v3
	v_sub_f32_e32 v21, v21, v75
	v_exp_f32_e32 v64, v5
	v_sub_f32_e32 v5, v26, v75
	v_add_f32_e32 v44, v33, v43
	v_exp_f32_e32 v21, v21
	v_exp_f32_e32 v65, v5
	v_sub_f32_e32 v5, v10, v75
	v_add_f32_e32 v44, 0, v44
	v_add_f32_e32 v45, v18, v56
	v_exp_f32_e32 v66, v5
	v_sub_f32_e32 v5, v27, v75
	v_add_f32_e32 v3, v45, v44
	v_add_f32_e32 v4, v19, v57
	v_exp_f32_e32 v67, v5
	v_sub_f32_e32 v5, v11, v75
	v_add_f32_e32 v3, v4, v3
	v_add_f32_e32 v4, v20, v58
	v_exp_f32_e32 v68, v5
	v_sub_f32_e32 v5, v28, v75
	v_add_f32_e32 v3, v4, v3
	v_add_f32_e32 v4, v21, v59
	v_exp_f32_e32 v69, v5
	v_sub_f32_e32 v5, v12, v75
	v_add_f32_e32 v3, v4, v3
	v_add_f32_e32 v4, v22, v60
	v_exp_f32_e32 v70, v5
	v_sub_f32_e32 v5, v29, v75
	v_add_f32_e32 v3, v4, v3
	v_add_f32_e32 v4, v23, v61
	v_exp_f32_e32 v71, v5
	v_sub_f32_e32 v5, v13, v75
	v_add_f32_e32 v3, v4, v3
	v_add_f32_e32 v4, v24, v62
	v_exp_f32_e32 v72, v5
	v_sub_f32_e32 v5, v30, v75
	v_add_f32_e32 v3, v4, v3
	v_add_f32_e32 v4, v63, v64
	v_exp_f32_e32 v73, v5
	v_sub_f32_e32 v5, v14, v75
	v_add_f32_e32 v3, v4, v3
	v_add_f32_e32 v4, v65, v66
	v_exp_f32_e32 v80, v5
	v_add_f32_e32 v3, v4, v3
	v_add_f32_e32 v4, v67, v68
	v_add_f32_e32 v3, v4, v3
	v_add_f32_e32 v4, v69, v70
	v_add_f32_e32 v3, v4, v3
	v_add_f32_e32 v4, v71, v72
	v_add_f32_e32 v3, v4, v3
	v_add_f32_e32 v4, v73, v80
	v_add_f32_e32 v3, v4, v3
	v_sub_f32_e32 v4, v31, v75
	v_exp_f32_e32 v81, v4
	v_sub_f32_e32 v4, v15, v75
	v_exp_f32_e32 v90, v4
	v_sub_f32_e32 v4, v32, v75
	v_exp_f32_e32 v91, v4
	v_sub_f32_e32 v4, v16, v75
	v_exp_f32_e32 v92, v4
	v_sub_f32_e32 v2, 0xf149f2ca, v75
	v_add_f32_e32 v4, v81, v90
	v_add_f32_e32 v3, v4, v3
	v_exp_f32_e32 v2, v2
	v_add_f32_e32 v4, v91, v92
	v_add_f32_e32 v76, v4, v3
	ds_bpermute_b32 v77, v197, v76
	v_cmp_gt_f32_e32 vcc, v17, v79
	s_cmp_lg_u64 vcc, 0
	v_mul_f32_e32 v78, 0, v2
	s_cselect_b64 vcc, -1, 0
	v_cndmask_b32_e32 v2, 0, v78, vcc
	v_mov_b32_e32 v3, v2
	v_mov_b32_e32 v4, v2
	v_mov_b32_e32 v5, v2
	v_mov_b32_e32 v6, v2
	v_mov_b32_e32 v7, v2
	v_mov_b32_e32 v8, v2
	v_mov_b32_e32 v9, v2
	v_mov_b32_e32 v10, v2
	v_mov_b32_e32 v11, v2
	v_mov_b32_e32 v12, v2
	v_mov_b32_e32 v13, v2
	v_mov_b32_e32 v14, v2
	v_mov_b32_e32 v15, v2
	v_mov_b32_e32 v16, v2
	v_mov_b32_e32 v17, v2
	ds_read_b64_tr_b16 v[44:45], v89 offset:12288
	ds_read_b64_tr_b16 v[46:47], v89 offset:13824
	ds_read_b64_tr_b16 v[50:51], v89 offset:13888
	ds_read_b64_tr_b16 v[48:49], v89 offset:12352
	v_cvt_pk_bf16_f32 v52, v33, v18
	v_cvt_pk_bf16_f32 v53, v19, v20
	v_cvt_pk_bf16_f32 v54, v21, v22
	v_cvt_pk_bf16_f32 v55, v23, v24
	s_nop 1
	v_mfma_f32_32x32x16_bf16 v[18:33], v[34:37], v[52:55], v[2:17]
	v_mfma_f32_32x32x16_bf16 v[2:17], v[38:41], v[52:55], v[2:17]
	ds_read_b64_tr_b16 v[34:35], v89 offset:15360
	ds_read_b64_tr_b16 v[36:37], v89 offset:16896
	ds_read_b64_tr_b16 v[40:41], v89 offset:16960
	ds_read_b64_tr_b16 v[38:39], v89 offset:15424
	v_cvt_pk_bf16_f32 v52, v63, v65
	v_cvt_pk_bf16_f32 v53, v67, v69
	v_cvt_pk_bf16_f32 v54, v71, v73
	v_cvt_pk_bf16_f32 v55, v81, v91
	s_waitcnt lgkmcnt(6)
	s_nop 0
	v_mfma_f32_32x32x16_bf16 v[18:33], v[44:47], v[52:55], v[18:33]
	s_waitcnt lgkmcnt(4)
	v_mfma_f32_32x32x16_bf16 v[2:17], v[48:51], v[52:55], v[2:17]
	ds_read_b64_tr_b16 v[44:45], v89 offset:18432
	ds_read_b64_tr_b16 v[46:47], v89 offset:19968
	ds_read_b64_tr_b16 v[50:51], v89 offset:20032
	ds_read_b64_tr_b16 v[48:49], v89 offset:18496
	v_cvt_pk_bf16_f32 v52, v43, v56
	v_cvt_pk_bf16_f32 v53, v57, v58
	v_cvt_pk_bf16_f32 v54, v59, v60
	v_cvt_pk_bf16_f32 v55, v61, v62
	s_waitcnt lgkmcnt(6)
	s_nop 0
	v_mfma_f32_32x32x16_bf16 v[18:33], v[34:37], v[52:55], v[18:33]
	s_waitcnt lgkmcnt(4)
	v_mfma_f32_32x32x16_bf16 v[2:17], v[38:41], v[52:55], v[2:17]
	v_cvt_pk_bf16_f32 v34, v64, v66
	v_cvt_pk_bf16_f32 v35, v68, v70
	v_cvt_pk_bf16_f32 v36, v72, v80
	v_cvt_pk_bf16_f32 v37, v90, v92
	s_waitcnt lgkmcnt(2)
	s_nop 0
	v_mfma_f32_32x32x16_bf16 v[18:33], v[44:47], v[34:37], v[18:33]
	s_waitcnt lgkmcnt(0)
	v_mfma_f32_32x32x16_bf16 v[2:17], v[48:51], v[34:37], v[2:17]
	ds_read_b128 v[34:37], v42 offset:21504
	ds_read_b128 v[66:69], v42 offset:21536
	ds_read_b128 v[38:41], v42 offset:26112
	ds_read_b128 v[70:73], v42 offset:26144
	ds_read_b128 v[90:93], v42 offset:21568
	ds_read_b128 v[94:97], v42 offset:21600
	ds_read_b128 v[114:117], v42 offset:26176
	ds_read_b128 v[118:121], v42 offset:26208
	s_waitcnt lgkmcnt(7)
	v_mfma_f32_32x32x16_bf16 v[50:65], v[34:37], v[98:101], 0
	s_waitcnt lgkmcnt(5)
	v_mfma_f32_32x32x16_bf16 v[34:49], v[38:41], v[98:101], 0
	v_mfma_f32_32x32x16_bf16 v[50:65], v[66:69], v[102:105], v[50:65]
	s_waitcnt lgkmcnt(4)
	v_mfma_f32_32x32x16_bf16 v[34:49], v[70:73], v[102:105], v[34:49]
	s_waitcnt lgkmcnt(3)
	v_mfma_f32_32x32x16_bf16 v[50:65], v[90:93], v[106:109], v[50:65]
	ds_read_b64_tr_b16 v[66:67], v89 offset:30720
	ds_read_b64_tr_b16 v[68:69], v89 offset:32256
	ds_read_b64_tr_b16 v[72:73], v89 offset:32320
	ds_read_b64_tr_b16 v[70:71], v89 offset:30784
	v_add_u32_e32 v81, 0xfffffbe1, v74
	v_cmp_lt_i32_e64 s[8:9], -1, v81
	v_cmp_gt_i32_e32 vcc, 16, v0
	s_and_b64 s[10:11], vcc, s[8:9]
	v_mov_b32_e32 v80, 0xf149f2ca
	s_waitcnt lgkmcnt(5)
	v_mfma_f32_32x32x16_bf16 v[34:49], v[114:117], v[106:109], v[34:49]
	v_mfma_f32_32x32x16_bf16 v[50:65], v[94:97], v[110:113], v[50:65]
	s_waitcnt lgkmcnt(4)
	v_mfma_f32_32x32x16_bf16 v[34:49], v[118:121], v[110:113], v[34:49]
	v_min_u32_e32 v210, 0x7f, v81
	v_lshl_add_u32 v210, v210, 2, s3
	v_cndmask_b32_e64 v210, v242, v210, s[10:11]
	ds_read_b32 v210, v210
	s_nop 6
	v_add_u32_e32 v150, 0xfffff9e1, v74
	v_cmp_lt_i32_e64 s[10:11], -1, v150
	v_cmp_gt_i32_e64 s[8:9], 8, v0
	s_and_b64 s[12:13], s[8:9], s[10:11]
	v_min_u32_e32 v211, 0x7f, v150
	v_lshl_add_u32 v211, v211, 2, s3
	v_cndmask_b32_e64 v211, v242, v211, s[12:13]
	ds_read_b32 v211, v211
	v_add_u32_e32 v81, 0xfffffbd1, v74
	v_cmp_lt_i32_e64 s[10:11], -1, v81
	s_and_b64 s[12:13], vcc, s[10:11]
	v_min_u32_e32 v212, 0x7f, v81
	v_lshl_add_u32 v212, v212, 2, s3
	v_cndmask_b32_e64 v212, v242, v212, s[12:13]
	ds_read_b32 v212, v212
	v_add_u32_e32 v151, 0xfffff9d1, v74
	v_cmp_lt_i32_e64 s[10:11], -1, v151
	s_and_b64 s[12:13], s[8:9], s[10:11]
	v_min_u32_e32 v213, 0x7f, v151
	v_lshl_add_u32 v213, v213, 2, s3
	v_cndmask_b32_e64 v213, v242, v213, s[12:13]
	ds_read_b32 v213, v213
	v_add_u32_e32 v81, 0xfffffbc1, v74
	v_cmp_lt_i32_e64 s[10:11], -1, v81
	s_and_b64 s[12:13], vcc, s[10:11]
	v_min_u32_e32 v214, 0x7f, v81
	v_lshl_add_u32 v214, v214, 2, s3
	v_cndmask_b32_e64 v214, v242, v214, s[12:13]
	ds_read_b32 v214, v214
	v_add_u32_e32 v152, 0xfffff9c1, v74
	v_cmp_lt_i32_e32 vcc, -1, v152
	s_and_b64 s[10:11], s[8:9], vcc
	v_min_u32_e32 v215, 0x7f, v152
	v_lshl_add_u32 v215, v215, 2, s3
	v_cndmask_b32_e64 v215, v242, v215, s[10:11]
	ds_read_b32 v215, v215
	v_add_u32_e32 v81, 0xfffffbb1, v74
	v_cmp_lt_i32_e32 vcc, -1, v81
	v_cmp_gt_i32_e64 s[8:9], 15, v0
	s_and_b64 s[10:11], s[8:9], vcc
	v_min_u32_e32 v216, 0x7f, v81
	v_lshl_add_u32 v216, v216, 2, s3
	v_cndmask_b32_e64 v216, v242, v216, s[10:11]
	ds_read_b32 v216, v216
	v_add_u32_e32 v153, 0xfffff9b1, v74
	v_cmp_lt_i32_e32 vcc, -1, v153
	v_cmp_gt_i32_e64 s[8:9], 7, v0
	s_and_b64 s[10:11], s[8:9], vcc
	v_min_u32_e32 v217, 0x7f, v153
	v_lshl_add_u32 v217, v217, 2, s3
	v_cndmask_b32_e64 v217, v242, v217, s[10:11]
	ds_read_b32 v217, v217
	v_add_u32_e32 v81, 0xfffffb61, v74
	v_cmp_lt_i32_e64 s[8:9], -1, v81
	v_cmp_gt_i32_e32 vcc, 14, v0
	s_and_b64 s[10:11], vcc, s[8:9]
	v_min_u32_e32 v218, 0x7f, v81
	v_lshl_add_u32 v218, v218, 2, s3
	v_cndmask_b32_e64 v218, v242, v218, s[10:11]
	ds_read_b32 v218, v218
	v_add_u32_e32 v154, 0xfffff961, v74
	v_cmp_lt_i32_e64 s[10:11], -1, v154
	v_cmp_gt_i32_e64 s[8:9], 6, v0
	s_and_b64 s[12:13], s[8:9], s[10:11]
	v_min_u32_e32 v219, 0x7f, v154
	v_lshl_add_u32 v219, v219, 2, s3
	v_cndmask_b32_e64 v219, v242, v219, s[12:13]
	ds_read_b32 v219, v219
	v_add_u32_e32 v81, 0xfffffb51, v74
	v_cmp_lt_i32_e64 s[10:11], -1, v81
	s_and_b64 s[12:13], vcc, s[10:11]
	v_min_u32_e32 v220, 0x7f, v81
	v_lshl_add_u32 v220, v220, 2, s3
	v_cndmask_b32_e64 v220, v242, v220, s[12:13]
	ds_read_b32 v220, v220
	v_add_u32_e32 v155, 0xfffff951, v74
	v_cmp_lt_i32_e64 s[10:11], -1, v155
	s_and_b64 s[12:13], s[8:9], s[10:11]
	v_min_u32_e32 v221, 0x7f, v155
	v_lshl_add_u32 v221, v221, 2, s3
	v_cndmask_b32_e64 v221, v242, v221, s[12:13]
	ds_read_b32 v221, v221
	v_add_u32_e32 v81, 0xfffffb41, v74
	v_cmp_lt_i32_e64 s[10:11], -1, v81
	s_and_b64 s[12:13], vcc, s[10:11]
	v_min_u32_e32 v222, 0x7f, v81
	v_lshl_add_u32 v222, v222, 2, s3
	v_cndmask_b32_e64 v222, v242, v222, s[12:13]
	ds_read_b32 v222, v222
	v_add_u32_e32 v156, 0xfffff941, v74
	v_cmp_lt_i32_e32 vcc, -1, v156
	s_and_b64 s[10:11], s[8:9], vcc
	v_min_u32_e32 v223, 0x7f, v156
	v_lshl_add_u32 v223, v223, 2, s3
	v_cndmask_b32_e64 v223, v242, v223, s[10:11]
	ds_read_b32 v223, v223
	v_add_u32_e32 v81, 0xfffffb31, v74
	v_cmp_lt_i32_e32 vcc, -1, v81
	v_cmp_gt_i32_e64 s[8:9], 13, v0
	s_and_b64 s[10:11], s[8:9], vcc
	v_min_u32_e32 v224, 0x7f, v81
	v_lshl_add_u32 v224, v224, 2, s3
	v_cndmask_b32_e64 v224, v242, v224, s[10:11]
	ds_read_b32 v224, v224
	v_add_u32_e32 v157, 0xfffff931, v74
	v_cmp_lt_i32_e32 vcc, -1, v157
	v_cmp_gt_i32_e64 s[8:9], 5, v0
	s_and_b64 s[10:11], s[8:9], vcc
	v_min_u32_e32 v225, 0x7f, v157
	v_lshl_add_u32 v225, v225, 2, s3
	v_cndmask_b32_e64 v225, v242, v225, s[10:11]
	ds_read_b32 v225, v225
	v_add_u32_e32 v81, 0xfffffae1, v74
	v_cmp_lt_i32_e64 s[8:9], -1, v81
	v_cmp_gt_i32_e32 vcc, 12, v0
	s_and_b64 s[10:11], vcc, s[8:9]
	v_min_u32_e32 v226, 0x7f, v81
	v_lshl_add_u32 v226, v226, 2, s3
	v_cndmask_b32_e64 v226, v242, v226, s[10:11]
	ds_read_b32 v226, v226
	v_add_u32_e32 v158, 0xfffff8e1, v74
	v_cmp_lt_i32_e64 s[10:11], -1, v158
	v_cmp_gt_i32_e64 s[8:9], 4, v0
	s_and_b64 s[12:13], s[8:9], s[10:11]
	v_min_u32_e32 v227, 0x7f, v158
	v_lshl_add_u32 v227, v227, 2, s3
	v_cndmask_b32_e64 v227, v242, v227, s[12:13]
	ds_read_b32 v227, v227
	v_add_u32_e32 v81, 0xfffffad1, v74
	v_cmp_lt_i32_e64 s[10:11], -1, v81
	s_and_b64 s[12:13], vcc, s[10:11]
	v_min_u32_e32 v228, 0x7f, v81
	v_lshl_add_u32 v228, v228, 2, s3
	v_cndmask_b32_e64 v228, v242, v228, s[12:13]
	ds_read_b32 v228, v228
	v_add_u32_e32 v159, 0xfffff8d1, v74
	v_cmp_lt_i32_e64 s[10:11], -1, v159
	s_and_b64 s[12:13], s[8:9], s[10:11]
	v_min_u32_e32 v229, 0x7f, v159
	v_lshl_add_u32 v229, v229, 2, s3
	v_cndmask_b32_e64 v229, v242, v229, s[12:13]
	ds_read_b32 v229, v229
	v_add_u32_e32 v81, 0xfffffac1, v74
	v_cmp_lt_i32_e64 s[10:11], -1, v81
	s_and_b64 s[12:13], vcc, s[10:11]
	v_min_u32_e32 v230, 0x7f, v81
	v_lshl_add_u32 v230, v230, 2, s3
	v_cndmask_b32_e64 v230, v242, v230, s[12:13]
	ds_read_b32 v230, v230
	v_add_u32_e32 v160, 0xfffff8c1, v74
	v_cmp_lt_i32_e32 vcc, -1, v160
	s_and_b64 s[10:11], s[8:9], vcc
	v_min_u32_e32 v231, 0x7f, v160
	v_lshl_add_u32 v231, v231, 2, s3
	v_cndmask_b32_e64 v231, v242, v231, s[10:11]
	ds_read_b32 v231, v231
	v_add_u32_e32 v81, 0xfffffab1, v74
	v_cmp_lt_i32_e32 vcc, -1, v81
	v_cmp_gt_i32_e64 s[8:9], 11, v0
	s_and_b64 s[10:11], s[8:9], vcc
	v_min_u32_e32 v232, 0x7f, v81
	v_lshl_add_u32 v232, v232, 2, s3
	v_cndmask_b32_e64 v232, v242, v232, s[10:11]
	ds_read_b32 v232, v232
	v_add_u32_e32 v161, 0xfffff8b1, v74
	v_cmp_lt_i32_e32 vcc, -1, v161
	v_cmp_gt_i32_e64 s[8:9], 3, v0
	s_and_b64 s[10:11], s[8:9], vcc
	v_min_u32_e32 v233, 0x7f, v161
	v_lshl_add_u32 v233, v233, 2, s3
	v_cndmask_b32_e64 v233, v242, v233, s[10:11]
	ds_read_b32 v233, v233
	v_add_u32_e32 v81, 0xfffffa61, v74
	v_cmp_lt_i32_e64 s[8:9], -1, v81
	v_cmp_gt_i32_e32 vcc, 10, v0
	s_and_b64 s[10:11], vcc, s[8:9]
	v_min_u32_e32 v234, 0x7f, v81
	v_lshl_add_u32 v234, v234, 2, s3
	v_cndmask_b32_e64 v234, v242, v234, s[10:11]
	ds_read_b32 v234, v234
	v_add_u32_e32 v162, 0xfffff861, v74
	v_cmp_lt_i32_e64 s[10:11], -1, v162
	v_cmp_gt_i32_e64 s[8:9], 2, v0
	s_and_b64 s[12:13], s[8:9], s[10:11]
	v_min_u32_e32 v235, 0x7f, v162
	v_lshl_add_u32 v235, v235, 2, s3
	v_cndmask_b32_e64 v235, v242, v235, s[12:13]
	ds_read_b32 v235, v235
	v_add_u32_e32 v81, 0xfffffa51, v74
	v_cmp_lt_i32_e64 s[10:11], -1, v81
	s_and_b64 s[12:13], vcc, s[10:11]
	v_min_u32_e32 v236, 0x7f, v81
	v_lshl_add_u32 v236, v236, 2, s3
	v_cndmask_b32_e64 v236, v242, v236, s[12:13]
	ds_read_b32 v236, v236
	v_add_u32_e32 v163, 0xfffff851, v74
	v_cmp_lt_i32_e64 s[10:11], -1, v163
	s_and_b64 s[12:13], s[8:9], s[10:11]
	v_min_u32_e32 v237, 0x7f, v163
	v_lshl_add_u32 v237, v237, 2, s3
	v_cndmask_b32_e64 v237, v242, v237, s[12:13]
	ds_read_b32 v237, v237
	v_add_u32_e32 v81, 0xfffffa41, v74
	v_cmp_lt_i32_e64 s[10:11], -1, v81
	s_and_b64 s[12:13], vcc, s[10:11]
	v_min_u32_e32 v238, 0x7f, v81
	v_lshl_add_u32 v238, v238, 2, s3
	v_cndmask_b32_e64 v238, v242, v238, s[12:13]
	ds_read_b32 v238, v238
	v_add_u32_e32 v164, 0xfffff841, v74
	v_cmp_lt_i32_e32 vcc, -1, v164
	s_and_b64 s[10:11], s[8:9], vcc
	v_min_u32_e32 v239, 0x7f, v164
	v_lshl_add_u32 v239, v239, 2, s3
	v_cndmask_b32_e64 v239, v242, v239, s[10:11]
	ds_read_b32 v239, v239
	v_add_u32_e32 v81, 0xfffffa31, v74
	v_cmp_lt_i32_e32 vcc, -1, v81
	v_cmp_gt_i32_e64 s[8:9], 9, v0
	s_and_b64 s[10:11], s[8:9], vcc
	v_min_u32_e32 v240, 0x7f, v81
	v_lshl_add_u32 v240, v240, 2, s3
	v_cndmask_b32_e64 v240, v242, v240, s[10:11]
	ds_read_b32 v240, v240
	v_add_u32_e32 v165, 0xfffff831, v74
	v_cmp_lt_i32_e32 vcc, -1, v165
	v_cmp_gt_i32_e64 s[8:9], 1, v0
	s_and_b64 s[10:11], s[8:9], vcc
	v_min_u32_e32 v241, 0x7f, v165
	v_lshl_add_u32 v241, v241, 2, s3
	v_cndmask_b32_e64 v241, v242, v241, s[10:11]
	ds_read_b32 v241, v241
	s_waitcnt lgkmcnt(0)
	v_add_f32_e32 v80, v50, v210
	v_add_f32_e32 v79, v34, v211
	v_add_f32_e32 v50, v51, v212
	v_add_f32_e32 v34, v35, v213
	v_add_f32_e32 v51, v52, v214
	v_add_f32_e32 v35, v36, v215
	v_add_f32_e32 v52, v53, v216
	v_add_f32_e32 v36, v37, v217
	v_add_f32_e32 v53, v54, v218
	v_add_f32_e32 v37, v38, v219
	v_add_f32_e32 v54, v55, v220
	v_add_f32_e32 v38, v39, v221
	v_add_f32_e32 v55, v56, v222
	v_add_f32_e32 v39, v40, v223
	v_add_f32_e32 v56, v57, v224
	v_add_f32_e32 v40, v41, v225
	v_add_f32_e32 v57, v58, v226
	v_add_f32_e32 v41, v42, v227
	v_add_f32_e32 v58, v59, v228
	v_add_f32_e32 v42, v43, v229
	v_add_f32_e32 v59, v60, v230
	v_add_f32_e32 v43, v44, v231
	v_add_f32_e32 v60, v61, v232
	v_add_f32_e32 v44, v45, v233
	v_add_f32_e32 v61, v62, v234
	v_add_f32_e32 v45, v46, v235
	v_add_f32_e32 v62, v63, v236
	v_add_f32_e32 v46, v47, v237
	v_add_f32_e32 v63, v64, v238
	v_add_f32_e32 v47, v48, v239
	v_add_f32_e32 v64, v65, v240
	v_add_f32_e32 v48, v49, v241
	v_max3_f32 v0, v191, v80, v79
	v_max_f32_e32 v65, v75, v75
	v_max3_f32 v0, v0, v50, v34
	v_max3_f32 v0, v0, v51, v35
	v_max3_f32 v0, v0, v52, v36
	v_max3_f32 v0, v0, v53, v37
	v_max3_f32 v0, v0, v54, v38
	v_max3_f32 v0, v0, v55, v39
	v_max3_f32 v0, v0, v56, v40
	v_max3_f32 v0, v0, v57, v41
	v_max3_f32 v0, v0, v58, v42
	v_max3_f32 v0, v0, v59, v43
	v_max3_f32 v0, v0, v60, v44
	v_max3_f32 v0, v0, v61, v45
	v_max3_f32 v0, v0, v62, v46
	v_max3_f32 v0, v0, v63, v47
	v_max3_f32 v0, v0, v64, v48
	ds_bpermute_b32 v49, v197, v0
	v_max_f32_e32 v0, v0, v0
	s_waitcnt lgkmcnt(0)
	v_max_f32_e32 v49, v49, v49
	v_max_f32_e32 v49, v0, v49
	v_max_f32_e32 v118, v65, v49
	v_sub_f32_e32 v35, v35, v118
	v_exp_f32_e32 v92, v35
	v_sub_f32_e32 v35, v52, v118
	v_exp_f32_e32 v125, v35
	v_sub_f32_e32 v35, v36, v118
	v_sub_f32_e32 v36, v53, v118
	v_exp_f32_e32 v136, v36
	v_sub_f32_e32 v36, v37, v118
	v_exp_f32_e32 v94, v36
	v_sub_f32_e32 v36, v54, v118
	v_exp_f32_e32 v138, v36
	v_sub_f32_e32 v36, v38, v118
	v_exp_f32_e32 v95, v36
	v_sub_f32_e32 v36, v55, v118
	v_exp_f32_e32 v141, v36
	v_sub_f32_e32 v36, v39, v118
	v_exp_f32_e32 v96, v36
	v_sub_f32_e32 v36, v56, v118
	v_sub_f32_e32 v0, v80, v118
	v_exp_f32_e32 v142, v36
	v_sub_f32_e32 v36, v40, v118
	v_sub_f32_e32 v65, v79, v118
	v_exp_f32_e32 v116, v0
	v_sub_f32_e32 v0, v50, v118
	v_exp_f32_e32 v97, v36
	v_sub_f32_e32 v36, v57, v118
	v_exp_f32_e32 v90, v65
	v_exp_f32_e32 v119, v0
	v_sub_f32_e32 v0, v34, v118
	v_exp_f32_e32 v120, v36
	v_sub_f32_e32 v36, v41, v118
	v_exp_f32_e32 v91, v0
	v_sub_f32_e32 v51, v51, v118
	v_exp_f32_e32 v114, v36
	v_sub_f32_e32 v36, v58, v118
	v_exp_f32_e32 v123, v51
	v_exp_f32_e32 v122, v36
	v_sub_f32_e32 v36, v42, v118
	v_exp_f32_e32 v93, v35
	v_exp_f32_e32 v115, v36
	v_sub_f32_e32 v36, v59, v118
	v_add_f32_e32 v34, v116, v90
	v_exp_f32_e32 v126, v36
	v_sub_f32_e32 v36, v43, v118
	v_add_f32_e32 v34, 0, v34
	v_add_f32_e32 v50, v119, v91
	v_exp_f32_e32 v117, v36
	v_sub_f32_e32 v36, v60, v118
	v_add_f32_e32 v34, v50, v34
	v_add_f32_e32 v35, v123, v92
	v_exp_f32_e32 v128, v36
	v_sub_f32_e32 v36, v44, v118
	v_add_f32_e32 v34, v35, v34
	v_add_f32_e32 v35, v125, v93
	v_exp_f32_e32 v121, v36
	v_sub_f32_e32 v36, v61, v118
	v_add_f32_e32 v34, v35, v34
	v_add_f32_e32 v35, v136, v94
	v_exp_f32_e32 v139, v36
	v_sub_f32_e32 v36, v45, v118
	v_add_f32_e32 v34, v35, v34
	v_add_f32_e32 v35, v138, v95
	v_exp_f32_e32 v124, v36
	v_sub_f32_e32 v36, v62, v118
	v_add_f32_e32 v34, v35, v34
	v_add_f32_e32 v35, v141, v96
	v_exp_f32_e32 v140, v36
	v_sub_f32_e32 v36, v46, v118
	v_add_f32_e32 v34, v35, v34
	v_add_f32_e32 v35, v142, v97
	v_exp_f32_e32 v127, v36
	v_sub_f32_e32 v36, v63, v118
	v_add_f32_e32 v34, v35, v34
	v_add_f32_e32 v35, v120, v114
	v_exp_f32_e32 v143, v36
	v_sub_f32_e32 v36, v47, v118
	v_add_f32_e32 v34, v35, v34
	v_add_f32_e32 v35, v122, v115
	v_exp_f32_e32 v129, v36
	v_sub_f32_e32 v36, v64, v118
	v_add_f32_e32 v34, v35, v34
	v_add_f32_e32 v35, v126, v117
	v_exp_f32_e32 v144, v36
	v_sub_f32_e32 v36, v48, v118
	v_add_f32_e32 v34, v35, v34
	v_add_f32_e32 v35, v128, v121
	v_exp_f32_e32 v137, v36
	v_add_f32_e32 v34, v35, v34
	v_add_f32_e32 v35, v139, v124
	v_add_f32_e32 v34, v35, v34
	v_add_f32_e32 v35, v140, v127
	v_add_f32_e32 v34, v35, v34
	v_add_f32_e32 v35, v143, v129
	v_add_f32_e32 v34, v35, v34
	v_add_f32_e32 v35, v144, v137
	v_add_f32_e32 v34, v35, v34
	v_sub_f32_e32 v0, v75, v118
	ds_bpermute_b32 v35, v197, v34
	v_exp_f32_e32 v0, v0
	v_cmp_gt_f32_e32 vcc, v49, v75
	s_cbranch_vccz .LBB0_1382
	v_pk_mul_f32 v[32:33], v[32:33], v[0:1] op_sel_hi:[1,0]
	v_pk_mul_f32 v[30:31], v[30:31], v[0:1] op_sel_hi:[1,0]
	v_pk_mul_f32 v[28:29], v[28:29], v[0:1] op_sel_hi:[1,0]
	v_pk_mul_f32 v[26:27], v[26:27], v[0:1] op_sel_hi:[1,0]
	v_pk_mul_f32 v[24:25], v[24:25], v[0:1] op_sel_hi:[1,0]
	v_pk_mul_f32 v[22:23], v[22:23], v[0:1] op_sel_hi:[1,0]
	v_pk_mul_f32 v[20:21], v[20:21], v[0:1] op_sel_hi:[1,0]
	v_pk_mul_f32 v[18:19], v[18:19], v[0:1] op_sel_hi:[1,0]
	v_pk_mul_f32 v[16:17], v[16:17], v[0:1] op_sel_hi:[1,0]
	v_pk_mul_f32 v[14:15], v[14:15], v[0:1] op_sel_hi:[1,0]
	v_pk_mul_f32 v[12:13], v[12:13], v[0:1] op_sel_hi:[1,0]
	v_pk_mul_f32 v[10:11], v[10:11], v[0:1] op_sel_hi:[1,0]
	v_pk_mul_f32 v[8:9], v[8:9], v[0:1] op_sel_hi:[1,0]
	v_pk_mul_f32 v[6:7], v[6:7], v[0:1] op_sel_hi:[1,0]
	v_pk_mul_f32 v[4:5], v[4:5], v[0:1] op_sel_hi:[1,0]
	v_pk_mul_f32 v[2:3], v[2:3], v[0:1] op_sel_hi:[1,0]

.LBB0_1416:
	v_cvt_pk_bf16_f32 v34, v116, v119
	v_cvt_pk_bf16_f32 v35, v123, v125
	v_cvt_pk_bf16_f32 v36, v136, v138
	v_cvt_pk_bf16_f32 v37, v141, v142
	s_mov_b32 s71, s67
	s_movk_i32 s8, 0x1000
	v_mfma_f32_32x32x16_bf16 v[18:33], v[66:69], v[34:37], v[18:33]
	v_cvt_pk_bf16_f32 v38, v114, v115
	v_cvt_pk_bf16_f32 v39, v117, v121
	v_cvt_pk_bf16_f32 v40, v124, v127
	v_cvt_pk_bf16_f32 v41, v129, v137
	v_lshl_add_u32 v200, v87, 2, 0
	v_add_u32_e32 v199, 0xa800, v200
	s_add_i32 s17, 0, 0x1c000
	v_mfma_f32_32x32x16_bf16 v[2:17], v[70:73], v[34:37], v[2:17]
	v_cvt_pk_bf16_f32 v34, v120, v122
	v_cvt_pk_bf16_f32 v35, v126, v128
	v_cvt_pk_bf16_f32 v36, v139, v140
	v_cvt_pk_bf16_f32 v37, v143, v144
	s_nop 1
	v_mfma_f32_32x32x16_bf16 v[18:33], v[74:77], v[34:37], v[18:33]
	v_mfma_f32_32x32x16_bf16 v[2:17], v[78:81], v[34:37], v[2:17]
	v_cvt_pk_bf16_f32 v34, v90, v91
	v_cvt_pk_bf16_f32 v35, v92, v93
	v_cvt_pk_bf16_f32 v36, v94, v95
	v_cvt_pk_bf16_f32 v37, v96, v97
	s_nop 1
	v_mfma_f32_32x32x16_bf16 v[18:33], v[62:65], v[34:37], v[18:33]
	v_mfma_f32_32x32x16_bf16 v[2:17], v[58:61], v[34:37], v[2:17]
	v_lshl_add_u64 v[34:35], v[82:83], 0, s[70:71]
	v_add_co_u32_e32 v36, vcc, s8, v34
	s_nop 1
	v_addc_co_u32_e32 v37, vcc, 0, v35, vcc
	v_mfma_f32_32x32x16_bf16 v[18:33], v[54:57], v[38:41], v[18:33]
	s_waitcnt vmcnt(0)
	v_lshlrev_b32_e32 v36, 16, v246
	v_mul_f32_e32 v36, 0xbfb8aa3b, v36
	v_exp_f32_e32 v36, v36
	v_mfma_f32_32x32x16_bf16 v[2:17], v[50:53], v[38:41], v[2:17]
	s_nop 6
	v_mul_f32_e64 v32, v0, v32
	v_mul_f32_e64 v33, v0, v33
	v_mul_f32_e64 v30, v0, v30
	v_mul_f32_e64 v31, v0, v31
	v_add_f32_e32 v36, 1.0, v36
	v_div_scale_f32 v37, s[8:9], v36, v36, 1.0
	v_rcp_f32_e32 v38, v37
	v_pk_mul_f32 v[28:29], v[0:1], v[28:29] op_sel_hi:[0,1]
	v_pk_mul_f32 v[26:27], v[0:1], v[26:27] op_sel_hi:[0,1]
	v_pk_mul_f32 v[24:25], v[0:1], v[24:25] op_sel_hi:[0,1]
	v_fma_f32 v39, -v37, v38, 1.0
	v_pk_mul_f32 v[22:23], v[0:1], v[22:23] op_sel_hi:[0,1]
	v_pk_mul_f32 v[20:21], v[0:1], v[20:21] op_sel_hi:[0,1]
	v_pk_mul_f32 v[18:19], v[0:1], v[18:19] op_sel_hi:[0,1]
	v_pk_mul_f32 v[16:17], v[0:1], v[16:17] op_sel_hi:[0,1]
	v_pk_mul_f32 v[14:15], v[0:1], v[14:15] op_sel_hi:[0,1]
	v_pk_mul_f32 v[12:13], v[0:1], v[12:13] op_sel_hi:[0,1]
	v_pk_mul_f32 v[10:11], v[0:1], v[10:11] op_sel_hi:[0,1]
	v_pk_mul_f32 v[8:9], v[0:1], v[8:9] op_sel_hi:[0,1]
	v_pk_mul_f32 v[6:7], v[0:1], v[6:7] op_sel_hi:[0,1]
	v_pk_mul_f32 v[4:5], v[0:1], v[4:5] op_sel_hi:[0,1]
	v_pk_mul_f32 v[2:3], v[0:1], v[2:3] op_sel_hi:[0,1]
	v_div_scale_f32 v0, vcc, 1.0, v36, 1.0
	v_fmac_f32_e32 v38, v39, v38
	v_mul_f32_e32 v39, v0, v38
	v_fma_f32 v40, -v37, v39, v0
	v_fmac_f32_e32 v39, v40, v38
	v_fma_f32 v0, -v37, v39, v0
	v_div_fmas_f32 v0, v0, v38, v39
	v_div_fixup_f32 v0, v0, v36, 1.0
	v_mul_f32_e32 v18, v18, v0
	v_mul_f32_e32 v19, v19, v0
	v_mul_f32_e32 v3, v3, v0
	v_mul_f32_e32 v5, v5, v0
	v_mul_f32_e32 v20, v20, v0
	v_mul_f32_e32 v4, v4, v0
	v_mul_f32_e32 v21, v21, v0
	v_mul_f32_e32 v22, v22, v0
	v_mul_f32_e32 v6, v6, v0
	v_mul_f32_e32 v23, v23, v0
	v_mul_f32_e32 v7, v7, v0
	v_mul_f32_e32 v24, v24, v0
	v_mul_f32_e32 v8, v8, v0
	v_mul_f32_e32 v25, v25, v0
	v_mul_f32_e32 v9, v9, v0
	v_mul_f32_e32 v26, v26, v0
	v_mul_f32_e32 v10, v10, v0
	v_mul_f32_e32 v27, v27, v0
	v_mul_f32_e32 v11, v11, v0
	v_mul_f32_e32 v28, v28, v0
	v_mul_f32_e32 v12, v12, v0
	v_mul_f32_e32 v29, v29, v0
	v_mul_f32_e32 v13, v13, v0
	v_mul_f32_e32 v30, v30, v0
	v_mul_f32_e32 v14, v14, v0
	ds_write2st64_b32 v200, v18, v19 offset0:168 offset1:176
	ds_write2st64_b32 v199, v3, v4 offset0:136 offset1:144
	ds_write2st64_b32 v200, v20, v21 offset0:184 offset1:192
	ds_write2st64_b32 v199, v5, v6 offset0:152 offset1:160
	ds_write2st64_b32 v200, v22, v23 offset0:200 offset1:208
	ds_write2st64_b32 v199, v7, v8 offset0:168 offset1:176
	ds_write2st64_b32 v200, v24, v25 offset0:216 offset1:224
	ds_write2st64_b32 v199, v9, v10 offset0:184 offset1:192
	ds_write2st64_b32 v200, v26, v27 offset0:232 offset1:240
	ds_write_b32 v200, v28 offset:63488
	ds_write2st64_b32 v199, v11, v12 offset0:200 offset1:208
	ds_write2st64_b32 v199, v29, v30 offset0:88 offset1:96
	ds_write2st64_b32 v199, v13, v14 offset0:216 offset1:224
	v_mul_f32_e32 v3, v31, v0
	v_mul_f32_e32 v5, v32, v0
	v_mul_f32_e32 v4, v15, v0
	ds_write2st64_b32 v199, v3, v5 offset0:104 offset1:112
	v_mul_f32_e32 v3, v16, v0
	v_mul_f32_e32 v2, v2, v0
	ds_write2st64_b32 v199, v4, v3 offset0:232 offset1:240
	v_mul_f32_e32 v3, v33, v0
	v_mul_f32_e32 v0, v17, v0
	ds_write_b32 v199, v0 offset:63488
	v_and_b32_e32 v0, 15, v84
	v_lshlrev_b32_e32 v8, 2, v0
	ds_write2st64_b32 v199, v3, v2 offset0:120 offset1:128
	v_ashrrev_i32_e32 v6, 4, v87
	s_movk_i32 s8, 0x204
	v_add_u32_e32 v2, -1, v8
	v_cmp_eq_u32_e32 vcc, 0, v0
	v_mul_lo_u32 v3, v6, s8
	v_add_u32_e32 v5, s17, v3
	v_cndmask_b32_e64 v7, v2, 0, vcc
	v_or_b32_e32 v2, 3, v8
	v_mov_b32_e32 v4, 0
	v_cmp_le_i32_e64 s[8:9], v7, v2
	v_mov_b32_e32 v9, 0
	s_waitcnt lgkmcnt(0)
	s_barrier
	s_and_saveexec_b64 s[10:11], s[8:9]
	s_cbranch_execz .LBB0_1426
	v_sub_u32_e32 v9, v8, v7
	v_add_u32_e32 v10, 4, v9
	v_cmp_lt_u32_e64 s[8:9], 1, v10
	s_mov_b64 s[14:15], -1
	v_mov_b32_e32 v9, 0
	s_and_saveexec_b64 s[12:13], s[8:9]
	s_cbranch_execz .LBB0_1421
	v_and_b32_e32 v11, -2, v10
	v_lshl_add_u32 v12, v7, 2, v5
	v_mov_b32_e32 v9, 0
	s_mov_b64 s[14:15], 0
	v_mov_b32_e32 v14, v11
	v_mov_b32_e32 v13, 0
